# grid barrier: non-leader workgroups poll the top-level generation word directly
# speedup vs baseline: 1.0113x; 1.0113x over previous
.LBB0_91:
	s_or_b64 exec, exec, s[8:9]
	v_cvt_f32_u32_e32 v4, v2
	s_waitcnt vmcnt(0)
	v_readfirstlane_b32 s3, v3
	v_sub_u32_e32 v3, 0, v2
	v_rcp_iflag_f32_e32 v4, v4
	v_add_u32_e32 v5, s3, v0
	v_mul_f32_e32 v4, 0x4f7ffffe, v4
	v_cvt_u32_f32_e32 v4, v4
	v_mul_lo_u32 v0, v3, v4
	v_mul_hi_u32 v0, v4, v0
	v_add_u32_e32 v0, v4, v0
	v_mul_hi_u32 v0, v5, v0
	v_mul_lo_u32 v3, v0, v2
	v_sub_u32_e32 v3, v5, v3
	v_add_u32_e32 v4, 1, v0
	v_cmp_ge_u32_e32 vcc, v3, v2
	s_nop 1
	v_cndmask_b32_e32 v0, v0, v4, vcc
	v_sub_u32_e32 v4, v3, v2
	v_cndmask_b32_e32 v3, v3, v4, vcc
	v_add_u32_e32 v4, 1, v0
	v_cmp_ge_u32_e32 vcc, v3, v2
	v_add_u32_e32 v3, 1, v5
	s_nop 0
	v_cndmask_b32_e32 v0, v0, v4, vcc
	v_mul_lo_u32 v4, v2, v0
	v_add_u32_e32 v2, v4, v2
	v_cmp_ne_u32_e32 vcc, v3, v2
	s_and_saveexec_b64 s[6:7], vcc
	s_xor_b64 s[6:7], exec, s[6:7]
	s_cbranch_execz .LBB0_105
	s_waitcnt lgkmcnt(0)
	s_add_u32 s22, s26, 0xf465600
	s_addc_u32 s23, s27, 0
	v_mov_b32_e32 v1, 0
	global_load_dword v1, v1, s[22:23] sc1
	s_waitcnt vmcnt(0)
	v_cmp_eq_u32_e32 vcc, v1, v0
	s_and_saveexec_b64 s[8:9], vcc
	s_cbranch_execz .LBB0_104
	s_add_u32 s20, s26, 0xf462300
	s_addc_u32 s21, s27, 0
	s_mov_b32 s3, 1
	s_mov_b64 s[24:25], 0
	v_mov_b32_e32 v1, 0
	s_branch .LBB0_95

.LBB0_303:
	s_or_b64 exec, exec, s[8:9]
	v_cvt_f32_u32_e32 v4, v2
	s_waitcnt vmcnt(0)
	v_readfirstlane_b32 s3, v3
	v_sub_u32_e32 v3, 0, v2
	v_rcp_iflag_f32_e32 v4, v4
	v_add_u32_e32 v5, s3, v0
	v_mul_f32_e32 v4, 0x4f7ffffe, v4
	v_cvt_u32_f32_e32 v4, v4
	v_mul_lo_u32 v0, v3, v4
	v_mul_hi_u32 v0, v4, v0
	v_add_u32_e32 v0, v4, v0
	v_mul_hi_u32 v0, v5, v0
	v_mul_lo_u32 v3, v0, v2
	v_sub_u32_e32 v3, v5, v3
	v_add_u32_e32 v4, 1, v0
	v_cmp_ge_u32_e32 vcc, v3, v2
	s_nop 1
	v_cndmask_b32_e32 v0, v0, v4, vcc
	v_sub_u32_e32 v4, v3, v2
	v_cndmask_b32_e32 v3, v3, v4, vcc
	v_add_u32_e32 v4, 1, v0
	v_cmp_ge_u32_e32 vcc, v3, v2
	v_add_u32_e32 v3, 1, v5
	s_nop 0
	v_cndmask_b32_e32 v0, v0, v4, vcc
	v_mul_lo_u32 v4, v2, v0
	v_add_u32_e32 v2, v4, v2
	v_cmp_ne_u32_e32 vcc, v3, v2
	s_and_saveexec_b64 s[6:7], vcc
	s_xor_b64 s[6:7], exec, s[6:7]
	s_cbranch_execz .LBB0_317
	s_waitcnt lgkmcnt(0)
	s_add_u32 s12, s26, 0xf465600
	s_addc_u32 s13, s27, 0
	v_mov_b32_e32 v1, 0
	global_load_dword v1, v1, s[12:13] sc1
	s_waitcnt vmcnt(0)
	v_cmp_eq_u32_e32 vcc, v1, v0
	s_and_saveexec_b64 s[8:9], vcc
	s_cbranch_execz .LBB0_316
	s_add_u32 s10, s26, 0xf462300
	s_addc_u32 s11, s27, 0
	s_mov_b32 s3, 1
	s_mov_b64 s[14:15], 0
	v_mov_b32_e32 v1, 0
	s_branch .LBB0_307

.LBB0_381:
	s_or_b64 exec, exec, s[8:9]
	v_cvt_f32_u32_e32 v5, v2
	s_waitcnt vmcnt(0)
	v_readfirstlane_b32 s6, v3
	v_sub_u32_e32 v3, 0, v2
	v_rcp_iflag_f32_e32 v5, v5
	v_add_u32_e32 v6, s6, v1
	v_mul_f32_e32 v5, 0x4f7ffffe, v5
	v_cvt_u32_f32_e32 v5, v5
	v_mul_lo_u32 v1, v3, v5
	v_mul_hi_u32 v1, v5, v1
	v_add_u32_e32 v1, v5, v1
	v_mul_hi_u32 v1, v6, v1
	v_mul_lo_u32 v3, v1, v2
	v_sub_u32_e32 v3, v6, v3
	v_add_u32_e32 v5, 1, v1
	v_cmp_ge_u32_e32 vcc, v3, v2
	s_nop 1
	v_cndmask_b32_e32 v1, v1, v5, vcc
	v_sub_u32_e32 v5, v3, v2
	v_cndmask_b32_e32 v3, v3, v5, vcc
	v_add_u32_e32 v5, 1, v1
	v_cmp_ge_u32_e32 vcc, v3, v2
	v_add_u32_e32 v3, 1, v6
	s_nop 0
	v_cndmask_b32_e32 v1, v1, v5, vcc
	v_mul_lo_u32 v5, v2, v1
	v_add_u32_e32 v2, v5, v2
	v_cmp_ne_u32_e32 vcc, v3, v2
	s_and_saveexec_b64 s[6:7], vcc
	s_xor_b64 s[6:7], exec, s[6:7]
	s_cbranch_execz .LBB0_395
	s_waitcnt lgkmcnt(0)
	s_add_u32 s10, s26, 0xf465600
	s_addc_u32 s11, s27, 0
	v_mov_b32_e32 v0, 0
	global_load_dword v0, v0, s[10:11] sc1
	s_waitcnt vmcnt(0)
	v_cmp_eq_u32_e32 vcc, v0, v1
	s_and_saveexec_b64 s[8:9], vcc
	s_cbranch_execz .LBB0_394
	s_mov_b32 s16, 1
	s_mov_b64 s[12:13], 0
	s_branch .LBB0_385

.LBB0_1629:
	s_or_b64 exec, exec, s[8:9]
	v_cvt_f32_u32_e32 v5, v2
	s_waitcnt vmcnt(0)
	v_readfirstlane_b32 s6, v3
	v_sub_u32_e32 v3, 0, v2
	v_rcp_iflag_f32_e32 v5, v5
	v_add_u32_e32 v6, s6, v1
	v_mul_f32_e32 v5, 0x4f7ffffe, v5
	v_cvt_u32_f32_e32 v5, v5
	v_mul_lo_u32 v1, v3, v5
	v_mul_hi_u32 v1, v5, v1
	v_add_u32_e32 v1, v5, v1
	v_mul_hi_u32 v1, v6, v1
	v_mul_lo_u32 v3, v1, v2
	v_sub_u32_e32 v3, v6, v3
	v_add_u32_e32 v5, 1, v1
	v_cmp_ge_u32_e32 vcc, v3, v2
	s_nop 1
	v_cndmask_b32_e32 v1, v1, v5, vcc
	v_sub_u32_e32 v5, v3, v2
	v_cndmask_b32_e32 v3, v3, v5, vcc
	v_add_u32_e32 v5, 1, v1
	v_cmp_ge_u32_e32 vcc, v3, v2
	v_add_u32_e32 v3, 1, v6
	s_nop 0
	v_cndmask_b32_e32 v1, v1, v5, vcc
	v_mul_lo_u32 v5, v2, v1
	v_add_u32_e32 v2, v5, v2
	v_cmp_ne_u32_e32 vcc, v3, v2
	s_and_saveexec_b64 s[6:7], vcc
	s_xor_b64 s[6:7], exec, s[6:7]
	s_cbranch_execz .LBB0_1643
	s_waitcnt lgkmcnt(0)
	s_add_u32 s10, s26, 0xf465600
	s_addc_u32 s11, s27, 0
	v_mov_b32_e32 v0, 0
	global_load_dword v0, v0, s[10:11] sc1
	s_waitcnt vmcnt(0)
	v_cmp_eq_u32_e32 vcc, v0, v1
	s_and_saveexec_b64 s[8:9], vcc
	s_cbranch_execz .LBB0_1642
	s_mov_b32 s22, 1
	s_mov_b64 s[12:13], 0
	s_branch .LBB0_1633
